# bL_k0M
# speedup vs baseline: 1.0145x; 1.0086x over previous
; #define PG8_STAGE(bufoff, gbase, voff) do { _Pragma("unroll") for (int _i = 0; _i < 2; ++_i) \
;         __builtin_amdgcn_global_load_lds((const unsigned*)((const char*)(gbase) + (voff)[_i]), (LAS unsigned*)(lds + (bufoff) + ldsw + _i * 8192), 16, 0, 0); } while (0)
; #define PG8_LDA(dst, b, h) do { _Pragma("unroll") for (int m = 0; m < 4; ++m) _Pragma("unroll") for (int k = 0; k < 2; ++k) dst[m][k] = *(const LAS bf16x8*)(lds + PG8_SA(b, h) + aoff + m * 2048 + k * 1024); } while (0)
; #define PG8_LDB(dst, b, h) do { _Pragma("unroll") for (int n = 0; n < 2; ++n) _Pragma("unroll") for (int k = 0; k < 2; ++k) dst[n][k] = *(const LAS bf16x8*)(lds + PG8_SB(b, h) + boff + n * 2048 + k * 1024); } while (0)
; #define PG8_MMA(ai, bj, At, Bt) do { __builtin_amdgcn_s_setprio(1); _Pragma("unroll") for (int m = 0; m < 4; ++m) _Pragma("unroll") for (int n = 0; n < 2; ++n) _Pragma("unroll") for (int k = 0; k < 2; ++k) \
;         acc[ai][bj][m][n] = __builtin_amdgcn_mfma_f32_16x16x32_bf16(Bt[n][k], At[m][k], acc[ai][bj][m][n], 0, 0, 0); __builtin_amdgcn_s_setprio(0); } while (0)
; #define PG8_WAIT_V(n) asm volatile("s_waitcnt vmcnt(" #n ")" ::: "memory")
; #define PG8_WAIT_L(n) asm volatile("s_waitcnt lgkmcnt(" #n ")" ::: "memory")
; #define PG8_BAR __builtin_amdgcn_s_barrier()
; #define PG8_SCHED __builtin_amdgcn_sched_barrier(0)
; template <class Epi, class Job>
; __device__ __forceinline__ void gemm_phase(LAS unsigned char* lds, const Job& S, const Epi& E) {
;     ...
;             PG8_LDB(B0, 0, 0); PG8_SCHED; PG8_LDA(At, 0, 0); PG8_STAGE(PG8_SA(1, 1), a1 + hstepA, voffA);
;             PG8_WAIT_L(8); PG8_BAR; PG8_WAIT_L(0); PG8_MMA(0, 0, At, B0); PG8_BAR; PG8_SCHED;
;             PG8_LDB(B1, 0, 1); PG8_STAGE(PG8_SB(0, 0), b2, voffB);
;             PG8_BAR; PG8_WAIT_L(0); PG8_MMA(0, 1, At, B1); PG8_BAR;
;             PG8_LDA(At, 0, 1); PG8_STAGE(PG8_SA(0, 0), a2, voffA);
;             PG8_BAR; PG8_WAIT_L(0); PG8_MMA(1, 0, At, B0); PG8_BAR; PG8_SCHED;
;             PG8_STAGE(PG8_SB(0, 1), b2 + hstepB, voffB);
;             PG8_WAIT_V(6); PG8_BAR; PG8_MMA(1, 1, At, B1); PG8_BAR;
;             PG8_LDB(B0, 1, 0); PG8_SCHED; PG8_LDA(At, 1, 0); PG8_STAGE(PG8_SA(0, 1), a2 + hstepA, voffA);
.LBB0_186:
	s_add_i32 m0, s52, 0xc000
	s_nop 0
	global_load_lds_dwordx4 v144, s[28:29]
	s_add_i32 m0, s52, 0xe000
	s_nop 0
	global_load_lds_dwordx4 v146, s[28:29]
	s_add_u32 s36, s28, 0xfff00080
	s_addc_u32 s37, s29, -1
	s_cmp_eq_u32 s68, 60
	s_cselect_b32 s47, s23, s37
	s_cselect_b32 s46, s22, s36
	s_cselect_b32 s37, s25, s67
	s_cselect_b32 s36, s24, s27
	ds_read_b128 v[190:193], v155 offset:1024
	ds_read_b128 v[198:201], v155 offset:3072
	ds_read_b128 v[206:209], v155 offset:5120
	ds_read_b128 v[214:217], v155 offset:7168
	s_waitcnt lgkmcnt(8)
	s_waitcnt lgkmcnt(0)
	s_setprio 1
	s_barrier
	v_mfma_f32_16x16x32_bf16 v[124:127], v[158:161], v[186:189], v[124:127]
	v_mfma_f32_16x16x32_bf16 v[120:123], v[178:181], v[186:189], v[120:123]
	v_mfma_f32_16x16x32_bf16 v[112:115], v[158:161], v[194:197], v[112:115]
	v_mfma_f32_16x16x32_bf16 v[104:107], v[178:181], v[194:197], v[104:107]
	v_mfma_f32_16x16x32_bf16 v[100:103], v[158:161], v[202:205], v[100:103]
	v_mfma_f32_16x16x32_bf16 v[92:95], v[178:181], v[202:205], v[92:95]
	v_mfma_f32_16x16x32_bf16 v[84:87], v[158:161], v[210:213], v[84:87]
	v_mfma_f32_16x16x32_bf16 v[76:79], v[178:181], v[210:213], v[76:79]
	v_mfma_f32_16x16x32_bf16 v[124:127], v[174:177], v[190:193], v[124:127]
	v_mfma_f32_16x16x32_bf16 v[120:123], v[182:185], v[190:193], v[120:123]
	v_mfma_f32_16x16x32_bf16 v[112:115], v[174:177], v[198:201], v[112:115]
	v_mfma_f32_16x16x32_bf16 v[104:107], v[182:185], v[198:201], v[104:107]
	v_mfma_f32_16x16x32_bf16 v[100:103], v[174:177], v[206:209], v[100:103]
	v_mfma_f32_16x16x32_bf16 v[92:95], v[182:185], v[206:209], v[92:95]
	v_mfma_f32_16x16x32_bf16 v[84:87], v[174:177], v[214:217], v[84:87]
	v_mfma_f32_16x16x32_bf16 v[76:79], v[182:185], v[214:217], v[76:79]
	s_barrier
	s_setprio 0
	ds_read_b128 v[218:221], v156
	ds_read_b128 v[222:225], v156 offset:1024
	ds_read_b128 v[226:229], v156 offset:2048
	ds_read_b128 v[230:233], v156 offset:3072
	s_add_i32 s69, s60, s49
	s_mov_b32 m0, s69
	s_nop 0
	global_load_lds_dwordx4 v136, s[36:37]
	s_add_i32 m0, s69, 0x2000
	s_nop 0
	global_load_lds_dwordx4 v140, s[36:37]
	s_waitcnt lgkmcnt(0)
	s_setprio 1
	s_barrier
	v_mfma_f32_16x16x32_bf16 v[116:119], v[218:221], v[186:189], v[116:119]
	v_mfma_f32_16x16x32_bf16 v[108:111], v[226:229], v[186:189], v[108:111]
	v_mfma_f32_16x16x32_bf16 v[96:99], v[218:221], v[194:197], v[96:99]
	v_mfma_f32_16x16x32_bf16 v[88:91], v[226:229], v[194:197], v[88:91]
	v_mfma_f32_16x16x32_bf16 v[80:83], v[218:221], v[202:205], v[80:83]
	v_mfma_f32_16x16x32_bf16 v[72:75], v[226:229], v[202:205], v[72:75]
	v_mfma_f32_16x16x32_bf16 v[68:71], v[218:221], v[210:213], v[68:71]
	v_mfma_f32_16x16x32_bf16 v[64:67], v[226:229], v[210:213], v[64:67]
	v_mfma_f32_16x16x32_bf16 v[116:119], v[222:225], v[190:193], v[116:119]
	ds_read_b128 v[186:189], v155 offset:16384
	v_mfma_f32_16x16x32_bf16 v[108:111], v[230:233], v[190:193], v[108:111]
	v_mfma_f32_16x16x32_bf16 v[96:99], v[222:225], v[198:201], v[96:99]
	ds_read_b128 v[194:197], v155 offset:18432
	v_mfma_f32_16x16x32_bf16 v[88:91], v[230:233], v[198:201], v[88:91]
	v_mfma_f32_16x16x32_bf16 v[80:83], v[222:225], v[206:209], v[80:83]
	ds_read_b128 v[202:205], v155 offset:20480
	v_mfma_f32_16x16x32_bf16 v[72:75], v[230:233], v[206:209], v[72:75]
	v_mfma_f32_16x16x32_bf16 v[68:71], v[222:225], v[214:217], v[68:71]
	ds_read_b128 v[210:213], v155 offset:22528
	v_mfma_f32_16x16x32_bf16 v[64:67], v[230:233], v[214:217], v[64:67]
	s_barrier
	s_setprio 0
	s_mov_b32 m0, s52
	s_mov_b64 s[100:101], s[46:47]
	global_load_lds_dwordx4 v134, s[46:47]
	s_mov_b32 m0, s53
	s_nop 0
	global_load_lds_dwordx4 v138, s[46:47]
	ds_read_b128 v[190:193], v155 offset:17408
	ds_read_b128 v[198:201], v155 offset:19456
	ds_read_b128 v[206:209], v155 offset:21504
	ds_read_b128 v[214:217], v155 offset:23552
	s_waitcnt vmcnt(8)
	s_waitcnt lgkmcnt(0)
	s_setprio 1
	s_barrier
	v_mfma_f32_16x16x32_bf16 v[60:63], v[158:161], v[186:189], v[60:63]
	v_mfma_f32_16x16x32_bf16 v[56:59], v[178:181], v[186:189], v[56:59]
	v_mfma_f32_16x16x32_bf16 v[52:55], v[158:161], v[194:197], v[52:55]
	v_mfma_f32_16x16x32_bf16 v[44:47], v[178:181], v[194:197], v[44:47]
	v_mfma_f32_16x16x32_bf16 v[36:39], v[158:161], v[202:205], v[36:39]
	v_mfma_f32_16x16x32_bf16 v[28:31], v[178:181], v[202:205], v[28:31]
	v_mfma_f32_16x16x32_bf16 v[20:23], v[158:161], v[210:213], v[20:23]
	v_mfma_f32_16x16x32_bf16 v[12:15], v[178:181], v[210:213], v[12:15]
	v_mfma_f32_16x16x32_bf16 v[60:63], v[174:177], v[190:193], v[60:63]
	v_mfma_f32_16x16x32_bf16 v[56:59], v[182:185], v[190:193], v[56:59]
	v_mfma_f32_16x16x32_bf16 v[52:55], v[174:177], v[198:201], v[52:55]
	v_mfma_f32_16x16x32_bf16 v[44:47], v[182:185], v[198:201], v[44:47]
	v_mfma_f32_16x16x32_bf16 v[36:39], v[174:177], v[206:209], v[36:39]
	v_mfma_f32_16x16x32_bf16 v[28:31], v[182:185], v[206:209], v[28:31]
	v_mfma_f32_16x16x32_bf16 v[20:23], v[174:177], v[214:217], v[20:23]
	v_mfma_f32_16x16x32_bf16 v[12:15], v[182:185], v[214:217], v[12:15]
	s_barrier
	s_setprio 0
	s_add_u32 s70, s36, 0x100000
	s_addc_u32 s71, s37, 0
	s_add_i32 s69, s61, s49
	s_mov_b32 m0, s69
	s_nop 0
	global_load_lds_dwordx4 v136, s[70:71]
	s_add_i32 m0, s69, 0x2000
	s_nop 0
	global_load_lds_dwordx4 v140, s[70:71]
	v_add_u32_e32 v157, 0x18000, v153
	ds_read_b128 v[158:161], v157
	ds_read_b128 v[174:177], v157 offset:1024
	ds_read_b128 v[178:181], v157 offset:2048
	ds_read_b128 v[182:185], v157 offset:3072
	s_waitcnt vmcnt(6)
	s_setprio 1
	s_barrier
; #define PG8_STAGE(bufoff, gbase, voff) do { _Pragma("unroll") for (int _i = 0; _i < 2; ++_i) \
;         __builtin_amdgcn_global_load_lds((const unsigned*)((const char*)(gbase) + (voff)[_i]), (LAS unsigned*)(lds + (bufoff) + ldsw + _i * 8192), 16, 0, 0); } while (0)
; #define PG8_LDA(dst, b, h) do { _Pragma("unroll") for (int m = 0; m < 4; ++m) _Pragma("unroll") for (int k = 0; k < 2; ++k) dst[m][k] = *(const LAS bf16x8*)(lds + PG8_SA(b, h) + aoff + m * 2048 + k * 1024); } while (0)
; #define PG8_LDB(dst, b, h) do { _Pragma("unroll") for (int n = 0; n < 2; ++n) _Pragma("unroll") for (int k = 0; k < 2; ++k) dst[n][k] = *(const LAS bf16x8*)(lds + PG8_SB(b, h) + boff + n * 2048 + k * 1024); } while (0)
; #define PG8_MMA(ai, bj, At, Bt) do { __builtin_amdgcn_s_setprio(1); _Pragma("unroll") for (int m = 0; m < 4; ++m) _Pragma("unroll") for (int n = 0; n < 2; ++n) _Pragma("unroll") for (int k = 0; k < 2; ++k) \
;         acc[ai][bj][m][n] = __builtin_amdgcn_mfma_f32_16x16x32_bf16(Bt[n][k], At[m][k], acc[ai][bj][m][n], 0, 0, 0); __builtin_amdgcn_s_setprio(0); } while (0)
; #define PG8_WAIT_L(n) asm volatile("s_waitcnt lgkmcnt(" #n ")" ::: "memory")
; #define PG8_BAR __builtin_amdgcn_s_barrier()
; #define PG8_SCHED __builtin_amdgcn_sched_barrier(0)
; template <class Epi, class Job>
; __device__ __forceinline__ void gemm_phase(LAS unsigned char* lds, const Job& S, const Epi& E) {
;     ...
;             PG8_LDB(B0, 1, 0); PG8_SCHED; PG8_LDA(At, 1, 0); PG8_STAGE(PG8_SA(0, 1), a2 + hstepA, voffA);
;             PG8_WAIT_L(8); PG8_BAR; PG8_WAIT_L(0); PG8_MMA(0, 0, At, B0); PG8_BAR; PG8_SCHED;
;             PG8_LDB(B1, 1, 1); PG8_STAGE(PG8_SB(1, 0), b3, voffB);
;             PG8_BAR; PG8_WAIT_L(0); PG8_MMA(0, 1, At, B1); PG8_BAR;
;             PG8_LDA(At, 1, 1); PG8_STAGE(PG8_SA(1, 0), a3, voffA);
	v_mfma_f32_16x16x32_bf16 v[48:51], v[218:221], v[186:189], v[48:51]
	v_mfma_f32_16x16x32_bf16 v[40:43], v[226:229], v[186:189], v[40:43]
	v_mfma_f32_16x16x32_bf16 v[32:35], v[218:221], v[194:197], v[32:35]
	v_mfma_f32_16x16x32_bf16 v[24:27], v[226:229], v[194:197], v[24:27]
	v_mfma_f32_16x16x32_bf16 v[16:19], v[218:221], v[202:205], v[16:19]
	v_mfma_f32_16x16x32_bf16 v[8:11], v[226:229], v[202:205], v[8:11]
	v_mfma_f32_16x16x32_bf16 v[4:7], v[218:221], v[210:213], v[4:7]
	v_mfma_f32_16x16x32_bf16 v[0:3], v[226:229], v[210:213], v[0:3]
	v_mfma_f32_16x16x32_bf16 v[48:51], v[222:225], v[190:193], v[48:51]
	ds_read_b128 v[186:189], v155 offset:32768
	v_mfma_f32_16x16x32_bf16 v[40:43], v[230:233], v[190:193], v[40:43]
	v_mfma_f32_16x16x32_bf16 v[32:35], v[222:225], v[198:201], v[32:35]
	ds_read_b128 v[194:197], v155 offset:34816
	v_mfma_f32_16x16x32_bf16 v[24:27], v[230:233], v[198:201], v[24:27]
	v_mfma_f32_16x16x32_bf16 v[16:19], v[222:225], v[206:209], v[16:19]
	ds_read_b128 v[202:205], v155 offset:36864
	v_mfma_f32_16x16x32_bf16 v[8:11], v[230:233], v[206:209], v[8:11]
	v_mfma_f32_16x16x32_bf16 v[4:7], v[222:225], v[214:217], v[4:7]
	ds_read_b128 v[210:213], v155 offset:38912
	v_mfma_f32_16x16x32_bf16 v[0:3], v[230:233], v[214:217], v[0:3]
	s_barrier
	s_setprio 0
	s_add_i32 s69, 0, 0x18000
	v_add_u32_e32 v157, s69, v153
	s_add_u32 s46, s46, 0x100000
	s_addc_u32 s47, s47, 0
	s_mov_b32 m0, s54
	s_nop 0
	global_load_lds_dwordx4 v134, s[46:47]
	s_mov_b32 m0, s55
	s_nop 0
	global_load_lds_dwordx4 v138, s[46:47]
	ds_read_b128 v[190:193], v155 offset:33792
	ds_read_b128 v[198:201], v155 offset:35840
	ds_read_b128 v[206:209], v155 offset:37888
	ds_read_b128 v[214:217], v155 offset:39936
	s_waitcnt lgkmcnt(8)
	s_waitcnt lgkmcnt(0)
	s_setprio 1
	v_add_u32_e32 v157, 0x1c000, v153
	s_barrier
	v_mfma_f32_16x16x32_bf16 v[124:127], v[158:161], v[186:189], v[124:127]
	v_mfma_f32_16x16x32_bf16 v[120:123], v[178:181], v[186:189], v[120:123]
	v_mfma_f32_16x16x32_bf16 v[112:115], v[158:161], v[194:197], v[112:115]
	v_mfma_f32_16x16x32_bf16 v[104:107], v[178:181], v[194:197], v[104:107]
	v_mfma_f32_16x16x32_bf16 v[100:103], v[158:161], v[202:205], v[100:103]
	v_mfma_f32_16x16x32_bf16 v[92:95], v[178:181], v[202:205], v[92:95]
	v_mfma_f32_16x16x32_bf16 v[84:87], v[158:161], v[210:213], v[84:87]
	v_mfma_f32_16x16x32_bf16 v[76:79], v[178:181], v[210:213], v[76:79]
	v_mfma_f32_16x16x32_bf16 v[124:127], v[174:177], v[190:193], v[124:127]
	v_mfma_f32_16x16x32_bf16 v[120:123], v[182:185], v[190:193], v[120:123]
	v_mfma_f32_16x16x32_bf16 v[112:115], v[174:177], v[198:201], v[112:115]
	v_mfma_f32_16x16x32_bf16 v[104:107], v[182:185], v[198:201], v[104:107]
	v_mfma_f32_16x16x32_bf16 v[100:103], v[174:177], v[206:209], v[100:103]
	v_mfma_f32_16x16x32_bf16 v[92:95], v[182:185], v[206:209], v[92:95]
	v_mfma_f32_16x16x32_bf16 v[84:87], v[174:177], v[214:217], v[84:87]
	v_mfma_f32_16x16x32_bf16 v[76:79], v[182:185], v[214:217], v[76:79]
	s_barrier
	s_setprio 0
	ds_read_b128 v[218:221], v157
	ds_read_b128 v[222:225], v157 offset:1024
	ds_read_b128 v[226:229], v157 offset:2048
	ds_read_b128 v[230:233], v157 offset:3072
	s_add_i32 s46, 0, 0x1c000
	s_add_i32 s47, s69, s49
	v_add_u32_e32 v157, s46, v153
	s_add_u32 s98, s36, s10
	s_addc_u32 s99, s37, s11
	s_mov_b32 m0, s47
	s_nop 0
	global_load_lds_dwordx4 v136, s[98:99]
	s_add_i32 m0, s47, 0x2000
	s_nop 0
	global_load_lds_dwordx4 v140, s[98:99]
	s_waitcnt lgkmcnt(0)
	s_setprio 1
	s_barrier
	v_mfma_f32_16x16x32_bf16 v[116:119], v[218:221], v[186:189], v[116:119]
	v_mfma_f32_16x16x32_bf16 v[108:111], v[226:229], v[186:189], v[108:111]
	v_mfma_f32_16x16x32_bf16 v[96:99], v[218:221], v[194:197], v[96:99]
	v_mfma_f32_16x16x32_bf16 v[88:91], v[226:229], v[194:197], v[88:91]
	v_mfma_f32_16x16x32_bf16 v[80:83], v[218:221], v[202:205], v[80:83]
	v_mfma_f32_16x16x32_bf16 v[72:75], v[226:229], v[202:205], v[72:75]
	v_mfma_f32_16x16x32_bf16 v[68:71], v[218:221], v[210:213], v[68:71]
	v_mfma_f32_16x16x32_bf16 v[64:67], v[226:229], v[210:213], v[64:67]
	v_mfma_f32_16x16x32_bf16 v[116:119], v[222:225], v[190:193], v[116:119]
	ds_read_b128 v[186:189], v155 offset:49152
	v_mfma_f32_16x16x32_bf16 v[108:111], v[230:233], v[190:193], v[108:111]
	v_mfma_f32_16x16x32_bf16 v[96:99], v[222:225], v[198:201], v[96:99]
	ds_read_b128 v[194:197], v155 offset:51200
	v_mfma_f32_16x16x32_bf16 v[88:91], v[230:233], v[198:201], v[88:91]
	v_mfma_f32_16x16x32_bf16 v[80:83], v[222:225], v[206:209], v[80:83]
	ds_read_b128 v[202:205], v155 offset:53248
	v_mfma_f32_16x16x32_bf16 v[72:75], v[230:233], v[206:209], v[72:75]
	v_mfma_f32_16x16x32_bf16 v[68:71], v[222:225], v[214:217], v[68:71]
	ds_read_b128 v[210:213], v155 offset:55296
	v_mfma_f32_16x16x32_bf16 v[64:67], v[230:233], v[214:217], v[64:67]
	s_barrier
; #define PG8_STAGE(bufoff, gbase, voff) do { _Pragma("unroll") for (int _i = 0; _i < 2; ++_i) \
;         __builtin_amdgcn_global_load_lds((const unsigned*)((const char*)(gbase) + (voff)[_i]), (LAS unsigned*)(lds + (bufoff) + ldsw + _i * 8192), 16, 0, 0); } while (0)
; #define PG8_LDA(dst, b, h) do { _Pragma("unroll") for (int m = 0; m < 4; ++m) _Pragma("unroll") for (int k = 0; k < 2; ++k) dst[m][k] = *(const LAS bf16x8*)(lds + PG8_SA(b, h) + aoff + m * 2048 + k * 1024); } while (0)
; #define PG8_LDB(dst, b, h) do { _Pragma("unroll") for (int n = 0; n < 2; ++n) _Pragma("unroll") for (int k = 0; k < 2; ++k) dst[n][k] = *(const LAS bf16x8*)(lds + PG8_SB(b, h) + boff + n * 2048 + k * 1024); } while (0)
; #define PG8_MMA(ai, bj, At, Bt) do { __builtin_amdgcn_s_setprio(1); _Pragma("unroll") for (int m = 0; m < 4; ++m) _Pragma("unroll") for (int n = 0; n < 2; ++n) _Pragma("unroll") for (int k = 0; k < 2; ++k) \
;         acc[ai][bj][m][n] = __builtin_amdgcn_mfma_f32_16x16x32_bf16(Bt[n][k], At[m][k], acc[ai][bj][m][n], 0, 0, 0); __builtin_amdgcn_s_setprio(0); } while (0)
;     __device__ __forceinline__ void operator()(const f32x4 (&acc)[2][2][4][2], const Unit& u, int wr, int wc, int fr, int fq) const {
;     ...
;         if (u.ocol < 6144) { const int sect = u.ocol >> 11, hh0 = (u.ocol & 2047) >> 7, b = u.orow >= SEQ ? 1 : 0;
;             base = qkv + (size_t)sect * MTOK * 2048 + ((size_t)(b * 16 + hh0) * SEQ + (row0 & (SEQ - 1))) * 128 + wc * 32 + 8 * fq; rstride = 128; bjstride = (size_t)SEQ * 128; }
;         else { base = proj2 + (size_t)row0 * NP2 + (u.ocol - 6144) + wc * 32 + 8 * fq; rstride = NP2; bjstride = HALF; }
; template <class Epi, class Job>
; __device__ __forceinline__ void gemm_phase(LAS unsigned char* lds, const Job& S, const Epi& E) {
;     ...
;             PG8_LDB(B0, 1, 0); PG8_SCHED; PG8_LDA(At, 1, 0); PG8_STAGE(PG8_SA(0, 1), a2 + hstepA, voffA);
;             PG8_WAIT_L(8); PG8_BAR; PG8_WAIT_L(0); PG8_MMA(0, 0, At, B0); PG8_BAR; PG8_SCHED;
;             PG8_LDB(B1, 1, 1); PG8_STAGE(PG8_SB(1, 0), b3, voffB);
;             PG8_BAR; PG8_WAIT_L(0); PG8_MMA(0, 1, At, B1); PG8_BAR;
;             PG8_LDA(At, 1, 1); PG8_STAGE(PG8_SA(1, 0), a3, voffA);
;             PG8_BAR; PG8_WAIT_L(0); PG8_MMA(1, 0, At, B0); PG8_BAR; PG8_SCHED;
;             PG8_STAGE(PG8_SB(1, 1), b3 + hstepB, voffB);
;             PG8_WAIT_V(6); PG8_BAR; PG8_MMA(1, 1, At, B1); PG8_BAR;
	s_setprio 0
	s_mov_b32 m0, s56
	s_add_u32 s100, s100, s10
	s_addc_u32 s101, s101, s11
	global_load_lds_dwordx4 v134, s[100:101]
	s_mov_b32 m0, s57
	s_nop 0
	global_load_lds_dwordx4 v138, s[100:101]
	ds_read_b128 v[190:193], v155 offset:50176
	ds_read_b128 v[198:201], v155 offset:52224
	ds_read_b128 v[206:209], v155 offset:54272
	ds_read_b128 v[214:217], v155 offset:56320
	s_waitcnt vmcnt(8)
	s_waitcnt lgkmcnt(0)
	s_setprio 1
	s_barrier
	v_mfma_f32_16x16x32_bf16 v[60:63], v[158:161], v[186:189], v[60:63]
	v_mfma_f32_16x16x32_bf16 v[56:59], v[178:181], v[186:189], v[56:59]
	v_mfma_f32_16x16x32_bf16 v[52:55], v[158:161], v[194:197], v[52:55]
	v_mfma_f32_16x16x32_bf16 v[44:47], v[178:181], v[194:197], v[44:47]
	v_mfma_f32_16x16x32_bf16 v[36:39], v[158:161], v[202:205], v[36:39]
	v_mfma_f32_16x16x32_bf16 v[28:31], v[178:181], v[202:205], v[28:31]
	v_mfma_f32_16x16x32_bf16 v[20:23], v[158:161], v[210:213], v[20:23]
	v_mfma_f32_16x16x32_bf16 v[12:15], v[178:181], v[210:213], v[12:15]
	v_mfma_f32_16x16x32_bf16 v[60:63], v[174:177], v[190:193], v[60:63]
	v_mfma_f32_16x16x32_bf16 v[56:59], v[182:185], v[190:193], v[56:59]
	v_mfma_f32_16x16x32_bf16 v[52:55], v[174:177], v[198:201], v[52:55]
	v_mfma_f32_16x16x32_bf16 v[44:47], v[182:185], v[198:201], v[44:47]
	v_mfma_f32_16x16x32_bf16 v[36:39], v[174:177], v[206:209], v[36:39]
	v_mfma_f32_16x16x32_bf16 v[28:31], v[182:185], v[206:209], v[28:31]
	v_mfma_f32_16x16x32_bf16 v[20:23], v[174:177], v[214:217], v[20:23]
	v_mfma_f32_16x16x32_bf16 v[12:15], v[182:185], v[214:217], v[12:15]
	s_barrier
	s_setprio 0
	s_add_u32 s36, s36, 0x100080
	s_addc_u32 s37, s37, 0
	s_add_i32 s46, s46, s49
	s_mov_b32 m0, s46
	s_nop 0
	global_load_lds_dwordx4 v136, s[36:37]
	s_add_i32 m0, s46, 0x2000
	s_nop 0
	global_load_lds_dwordx4 v140, s[36:37]
	ds_read_b128 v[158:161], v154
	ds_read_b128 v[174:177], v154 offset:1024
	ds_read_b128 v[178:181], v154 offset:2048
	ds_read_b128 v[182:185], v154 offset:3072
	s_waitcnt vmcnt(6)
	s_setprio 1
	s_barrier
	v_mfma_f32_16x16x32_bf16 v[48:51], v[218:221], v[186:189], v[48:51]
	v_mfma_f32_16x16x32_bf16 v[40:43], v[226:229], v[186:189], v[40:43]
	v_mfma_f32_16x16x32_bf16 v[32:35], v[218:221], v[194:197], v[32:35]
	v_mfma_f32_16x16x32_bf16 v[24:27], v[226:229], v[194:197], v[24:27]
	v_mfma_f32_16x16x32_bf16 v[16:19], v[218:221], v[202:205], v[16:19]
	v_mfma_f32_16x16x32_bf16 v[8:11], v[226:229], v[202:205], v[8:11]
	v_mfma_f32_16x16x32_bf16 v[4:7], v[218:221], v[210:213], v[4:7]
	v_mfma_f32_16x16x32_bf16 v[0:3], v[226:229], v[210:213], v[0:3]
	v_mfma_f32_16x16x32_bf16 v[48:51], v[222:225], v[190:193], v[48:51]
	ds_read_b128 v[186:189], v155
	v_mfma_f32_16x16x32_bf16 v[40:43], v[230:233], v[190:193], v[40:43]
	v_mfma_f32_16x16x32_bf16 v[32:35], v[222:225], v[198:201], v[32:35]
	ds_read_b128 v[194:197], v155 offset:2048
	v_mfma_f32_16x16x32_bf16 v[24:27], v[230:233], v[198:201], v[24:27]
	v_mfma_f32_16x16x32_bf16 v[16:19], v[222:225], v[206:209], v[16:19]
	ds_read_b128 v[202:205], v155 offset:4096
	v_mfma_f32_16x16x32_bf16 v[8:11], v[230:233], v[206:209], v[8:11]
	v_mfma_f32_16x16x32_bf16 v[4:7], v[222:225], v[214:217], v[4:7]
	ds_read_b128 v[210:213], v155 offset:6144
	v_mfma_f32_16x16x32_bf16 v[0:3], v[230:233], v[214:217], v[0:3]
	s_barrier
	s_setprio 0
	s_add_i32 s68, s68, 2
	s_add_u32 s28, s28, 0x100
	s_addc_u32 s29, s29, 0
	s_add_u32 s27, s27, 0x100
	s_addc_u32 s67, s67, 0
	s_cmp_gt_u32 s68, 61
	s_cbranch_scc0 .LBB0_186
	s_waitcnt lgkmcnt(0)
	v_add_u32_e32 v157, s66, v131
	s_cmpk_gt_i32 s26, 0x17ff
	s_mov_b64 s[28:29], -1
	s_cbranch_scc0 .LBB0_189
	v_mov_b64_e32 v[150:151], s[20:21]
	v_mad_i64_i32 v[150:151], s[28:29], v157, s62, v[150:151]
	s_mov_b32 s27, s9
	v_lshl_add_u64 v[150:151], s[26:27], 1, v[150:151]
	v_lshl_add_u64 v[150:151], v[150:151], 0, s[12:13]
	s_mov_b64 s[28:29], 0

; #define PG8_STAGE(bufoff, gbase, voff) do { _Pragma("unroll") for (int _i = 0; _i < 2; ++_i) \
;         __builtin_amdgcn_global_load_lds((const unsigned*)((const char*)(gbase) + (voff)[_i]), (LAS unsigned*)(lds + (bufoff) + ldsw + _i * 8192), 16, 0, 0); } while (0)
; #define PG8_LDA(dst, b, h) do { _Pragma("unroll") for (int m = 0; m < 4; ++m) _Pragma("unroll") for (int k = 0; k < 2; ++k) dst[m][k] = *(const LAS bf16x8*)(lds + PG8_SA(b, h) + aoff + m * 2048 + k * 1024); } while (0)
; #define PG8_LDB(dst, b, h) do { _Pragma("unroll") for (int n = 0; n < 2; ++n) _Pragma("unroll") for (int k = 0; k < 2; ++k) dst[n][k] = *(const LAS bf16x8*)(lds + PG8_SB(b, h) + boff + n * 2048 + k * 1024); } while (0)
; #define PG8_WAIT_V(n) asm volatile("s_waitcnt vmcnt(" #n ")" ::: "memory")
; #define PG8_WAIT_L(n) asm volatile("s_waitcnt lgkmcnt(" #n ")" ::: "memory")
; #define PG8_BAR __builtin_amdgcn_s_barrier()
; #define PG8_SCHED __builtin_amdgcn_sched_barrier(0)
; template <class Epi, class Job>
; __device__ __forceinline__ void gemm_phase(LAS unsigned char* lds, const Job& S, const Epi& E) {
;     ...
;             PG8_LDB(B0, 0, 0); PG8_SCHED; PG8_LDA(At, 0, 0); PG8_STAGE(PG8_SA(1, 1), a1 + hstepA, voffA);
;             PG8_WAIT_L(8); PG8_BAR; PG8_WAIT_L(0); PG8_MMA(0, 0, At, B0); PG8_BAR; PG8_SCHED;
;             PG8_LDB(B1, 0, 1); PG8_STAGE(PG8_SB(0, 0), b2, voffB);
;             PG8_BAR; PG8_WAIT_L(0); PG8_MMA(0, 1, At, B1); PG8_BAR;
;             PG8_LDA(At, 0, 1); PG8_STAGE(PG8_SA(0, 0), a2, voffA);
;             PG8_BAR; PG8_WAIT_L(0); PG8_MMA(1, 0, At, B0); PG8_BAR; PG8_SCHED;
;             PG8_STAGE(PG8_SB(0, 1), b2 + hstepB, voffB);
;             PG8_WAIT_V(6); PG8_BAR; PG8_MMA(1, 1, At, B1); PG8_BAR;
;             PG8_LDB(B0, 1, 0); PG8_SCHED; PG8_LDA(At, 1, 0); PG8_STAGE(PG8_SA(0, 1), a2 + hstepA, voffA);
;             PG8_WAIT_L(8); PG8_BAR; PG8_WAIT_L(0); PG8_MMA(0, 0, At, B0); PG8_BAR; PG8_SCHED;
;             PG8_LDB(B1, 1, 1); PG8_STAGE(PG8_SB(1, 0), b3, voffB);
;             PG8_BAR; PG8_WAIT_L(0); PG8_MMA(0, 1, At, B1); PG8_BAR;
;             PG8_LDA(At, 1, 1); PG8_STAGE(PG8_SA(1, 0), a3, voffA);
;             PG8_BAR; PG8_WAIT_L(0); PG8_MMA(1, 0, At, B0); PG8_BAR; PG8_SCHED;
;             PG8_STAGE(PG8_SB(1, 1), b3 + hstepB, voffB);
;             PG8_WAIT_V(6); PG8_BAR; PG8_MMA(1, 1, At, B1); PG8_BAR;
.LBB0_457:
	s_add_i32 m0, s57, 0xc000
	s_nop 0
	global_load_lds_dwordx4 v132, s[36:37]
	s_add_i32 m0, s57, 0xe000
	s_nop 0
	global_load_lds_dwordx4 v142, s[36:37]
	s_add_u32 s46, s36, 0xfff00080
	s_addc_u32 s47, s37, -1
	s_cmp_eq_u32 s81, 60
	s_cselect_b32 s49, s29, s47
	s_cselect_b32 s48, s28, s46
	s_cselect_b32 s47, s31, s80
	s_cselect_b32 s46, s30, s79
	ds_read_b128 v[174:177], v151 offset:1024
	ds_read_b128 v[182:185], v151 offset:3072
	ds_read_b128 v[190:193], v151 offset:5120
	ds_read_b128 v[198:201], v151 offset:7168
	s_waitcnt lgkmcnt(8)
	s_waitcnt lgkmcnt(0)
	s_setprio 1
	s_barrier
	v_mfma_f32_16x16x32_bf16 v[124:127], v[154:157], v[170:173], v[124:127]
	v_mfma_f32_16x16x32_bf16 v[120:123], v[162:165], v[170:173], v[120:123]
	v_mfma_f32_16x16x32_bf16 v[116:119], v[154:157], v[178:181], v[116:119]
	v_mfma_f32_16x16x32_bf16 v[108:111], v[162:165], v[178:181], v[108:111]
	v_mfma_f32_16x16x32_bf16 v[100:103], v[154:157], v[186:189], v[100:103]
	v_mfma_f32_16x16x32_bf16 v[92:95], v[162:165], v[186:189], v[92:95]
	v_mfma_f32_16x16x32_bf16 v[84:87], v[154:157], v[194:197], v[84:87]
	v_mfma_f32_16x16x32_bf16 v[76:79], v[162:165], v[194:197], v[76:79]
	v_mfma_f32_16x16x32_bf16 v[124:127], v[158:161], v[174:177], v[124:127]
	v_mfma_f32_16x16x32_bf16 v[120:123], v[166:169], v[174:177], v[120:123]
	v_mfma_f32_16x16x32_bf16 v[116:119], v[158:161], v[182:185], v[116:119]
	v_mfma_f32_16x16x32_bf16 v[108:111], v[166:169], v[182:185], v[108:111]
	v_mfma_f32_16x16x32_bf16 v[100:103], v[158:161], v[190:193], v[100:103]
	v_mfma_f32_16x16x32_bf16 v[92:95], v[166:169], v[190:193], v[92:95]
	v_mfma_f32_16x16x32_bf16 v[84:87], v[158:161], v[198:201], v[84:87]
	v_mfma_f32_16x16x32_bf16 v[76:79], v[166:169], v[198:201], v[76:79]
	s_barrier
	s_setprio 0
	ds_read_b128 v[202:205], v152
	ds_read_b128 v[206:209], v152 offset:1024
	ds_read_b128 v[210:213], v152 offset:2048
	ds_read_b128 v[214:217], v152 offset:3072
	s_add_i32 s82, s66, s56
	s_mov_b32 m0, s82
	s_nop 0
	global_load_lds_dwordx4 v136, s[46:47]
	s_add_i32 m0, s82, 0x2000
	s_nop 0
	global_load_lds_dwordx4 v140, s[46:47]
	s_waitcnt lgkmcnt(0)
	s_setprio 1
	s_barrier
	v_mfma_f32_16x16x32_bf16 v[112:115], v[202:205], v[170:173], v[112:115]
	v_mfma_f32_16x16x32_bf16 v[104:107], v[210:213], v[170:173], v[104:107]
	v_mfma_f32_16x16x32_bf16 v[96:99], v[202:205], v[178:181], v[96:99]
	v_mfma_f32_16x16x32_bf16 v[88:91], v[210:213], v[178:181], v[88:91]
	v_mfma_f32_16x16x32_bf16 v[80:83], v[202:205], v[186:189], v[80:83]
	v_mfma_f32_16x16x32_bf16 v[72:75], v[210:213], v[186:189], v[72:75]
	v_mfma_f32_16x16x32_bf16 v[68:71], v[202:205], v[194:197], v[68:71]
	v_mfma_f32_16x16x32_bf16 v[64:67], v[210:213], v[194:197], v[64:67]
	v_mfma_f32_16x16x32_bf16 v[112:115], v[206:209], v[174:177], v[112:115]
	ds_read_b128 v[170:173], v151 offset:16384
	v_mfma_f32_16x16x32_bf16 v[104:107], v[214:217], v[174:177], v[104:107]
	v_mfma_f32_16x16x32_bf16 v[96:99], v[206:209], v[182:185], v[96:99]
	ds_read_b128 v[178:181], v151 offset:18432
	v_mfma_f32_16x16x32_bf16 v[88:91], v[214:217], v[182:185], v[88:91]
	v_mfma_f32_16x16x32_bf16 v[80:83], v[206:209], v[190:193], v[80:83]
	ds_read_b128 v[186:189], v151 offset:20480
	v_mfma_f32_16x16x32_bf16 v[72:75], v[214:217], v[190:193], v[72:75]
	v_mfma_f32_16x16x32_bf16 v[68:71], v[206:209], v[198:201], v[68:71]
	ds_read_b128 v[194:197], v151 offset:22528
	v_mfma_f32_16x16x32_bf16 v[64:67], v[214:217], v[198:201], v[64:67]
	s_barrier
	s_setprio 0
	s_mov_b32 m0, s57
	s_mov_b64 s[100:101], s[48:49]
	global_load_lds_dwordx4 v134, s[48:49]
	s_mov_b32 m0, s58
	s_nop 0
	global_load_lds_dwordx4 v138, s[48:49]
	ds_read_b128 v[174:177], v151 offset:17408
	ds_read_b128 v[182:185], v151 offset:19456
	ds_read_b128 v[190:193], v151 offset:21504
	ds_read_b128 v[198:201], v151 offset:23552
	s_waitcnt vmcnt(8)
	s_waitcnt lgkmcnt(0)
	s_setprio 1
	s_barrier
	v_mfma_f32_16x16x32_bf16 v[60:63], v[154:157], v[170:173], v[60:63]
	v_mfma_f32_16x16x32_bf16 v[56:59], v[162:165], v[170:173], v[56:59]
	v_mfma_f32_16x16x32_bf16 v[52:55], v[154:157], v[178:181], v[52:55]
	v_mfma_f32_16x16x32_bf16 v[44:47], v[162:165], v[178:181], v[44:47]
	v_mfma_f32_16x16x32_bf16 v[36:39], v[154:157], v[186:189], v[36:39]
	v_mfma_f32_16x16x32_bf16 v[28:31], v[162:165], v[186:189], v[28:31]
	v_mfma_f32_16x16x32_bf16 v[20:23], v[154:157], v[194:197], v[20:23]
	v_mfma_f32_16x16x32_bf16 v[12:15], v[162:165], v[194:197], v[12:15]
	v_mfma_f32_16x16x32_bf16 v[60:63], v[158:161], v[174:177], v[60:63]
	v_mfma_f32_16x16x32_bf16 v[56:59], v[166:169], v[174:177], v[56:59]
	v_mfma_f32_16x16x32_bf16 v[52:55], v[158:161], v[182:185], v[52:55]
	v_mfma_f32_16x16x32_bf16 v[44:47], v[166:169], v[182:185], v[44:47]
	v_mfma_f32_16x16x32_bf16 v[36:39], v[158:161], v[190:193], v[36:39]
	v_mfma_f32_16x16x32_bf16 v[28:31], v[166:169], v[190:193], v[28:31]
	v_mfma_f32_16x16x32_bf16 v[20:23], v[158:161], v[198:201], v[20:23]
	v_mfma_f32_16x16x32_bf16 v[12:15], v[166:169], v[198:201], v[12:15]
	s_barrier
	s_setprio 0
	s_add_u32 s82, s46, 0x100000
	s_addc_u32 s83, s47, 0
	s_add_i32 s84, s67, s56
	s_mov_b32 m0, s84
	s_nop 0
	global_load_lds_dwordx4 v136, s[82:83]
	s_add_i32 m0, s84, 0x2000
	s_nop 0
	global_load_lds_dwordx4 v140, s[82:83]
	v_add_u32_e32 v153, 0x18000, v148
	ds_read_b128 v[154:157], v153
	ds_read_b128 v[158:161], v153 offset:1024
	ds_read_b128 v[162:165], v153 offset:2048
	ds_read_b128 v[166:169], v153 offset:3072
	s_waitcnt vmcnt(6)
	s_setprio 1
	s_barrier
; #define PG8_STAGE(bufoff, gbase, voff) do { _Pragma("unroll") for (int _i = 0; _i < 2; ++_i) \
;         __builtin_amdgcn_global_load_lds((const unsigned*)((const char*)(gbase) + (voff)[_i]), (LAS unsigned*)(lds + (bufoff) + ldsw + _i * 8192), 16, 0, 0); } while (0)
; #define PG8_LDA(dst, b, h) do { _Pragma("unroll") for (int m = 0; m < 4; ++m) _Pragma("unroll") for (int k = 0; k < 2; ++k) dst[m][k] = *(const LAS bf16x8*)(lds + PG8_SA(b, h) + aoff + m * 2048 + k * 1024); } while (0)
; #define PG8_LDB(dst, b, h) do { _Pragma("unroll") for (int n = 0; n < 2; ++n) _Pragma("unroll") for (int k = 0; k < 2; ++k) dst[n][k] = *(const LAS bf16x8*)(lds + PG8_SB(b, h) + boff + n * 2048 + k * 1024); } while (0)
; #define PG8_WAIT_V(n) asm volatile("s_waitcnt vmcnt(" #n ")" ::: "memory")
; #define PG8_WAIT_L(n) asm volatile("s_waitcnt lgkmcnt(" #n ")" ::: "memory")
; #define PG8_BAR __builtin_amdgcn_s_barrier()
; #define PG8_SCHED __builtin_amdgcn_sched_barrier(0)
; template <class Epi, class Job>
; __device__ __forceinline__ void gemm_phase(LAS unsigned char* lds, const Job& S, const Epi& E) {
;     ...
;             PG8_LDB(B0, 0, 0); PG8_SCHED; PG8_LDA(At, 0, 0); PG8_STAGE(PG8_SA(1, 1), a1 + hstepA, voffA);
;             PG8_WAIT_L(8); PG8_BAR; PG8_WAIT_L(0); PG8_MMA(0, 0, At, B0); PG8_BAR; PG8_SCHED;
;             PG8_LDB(B1, 0, 1); PG8_STAGE(PG8_SB(0, 0), b2, voffB);
;             PG8_BAR; PG8_WAIT_L(0); PG8_MMA(0, 1, At, B1); PG8_BAR;
;             PG8_LDA(At, 0, 1); PG8_STAGE(PG8_SA(0, 0), a2, voffA);
;             PG8_BAR; PG8_WAIT_L(0); PG8_MMA(1, 0, At, B0); PG8_BAR; PG8_SCHED;
;             PG8_STAGE(PG8_SB(0, 1), b2 + hstepB, voffB);
;             PG8_WAIT_V(6); PG8_BAR; PG8_MMA(1, 1, At, B1); PG8_BAR;
;             PG8_LDB(B0, 1, 0); PG8_SCHED; PG8_LDA(At, 1, 0); PG8_STAGE(PG8_SA(0, 1), a2 + hstepA, voffA);
;             PG8_WAIT_L(8); PG8_BAR; PG8_WAIT_L(0); PG8_MMA(0, 0, At, B0); PG8_BAR; PG8_SCHED;
;             PG8_LDB(B1, 1, 1); PG8_STAGE(PG8_SB(1, 0), b3, voffB);
;             PG8_BAR; PG8_WAIT_L(0); PG8_MMA(0, 1, At, B1); PG8_BAR;
;             PG8_LDA(At, 1, 1); PG8_STAGE(PG8_SA(1, 0), a3, voffA);
;             PG8_BAR; PG8_WAIT_L(0); PG8_MMA(1, 0, At, B0); PG8_BAR; PG8_SCHED;
;             PG8_STAGE(PG8_SB(1, 1), b3 + hstepB, voffB);
;             PG8_WAIT_V(6); PG8_BAR; PG8_MMA(1, 1, At, B1); PG8_BAR;
	v_mfma_f32_16x16x32_bf16 v[48:51], v[202:205], v[170:173], v[48:51]
	v_mfma_f32_16x16x32_bf16 v[40:43], v[210:213], v[170:173], v[40:43]
	v_mfma_f32_16x16x32_bf16 v[32:35], v[202:205], v[178:181], v[32:35]
	v_mfma_f32_16x16x32_bf16 v[24:27], v[210:213], v[178:181], v[24:27]
	v_mfma_f32_16x16x32_bf16 v[16:19], v[202:205], v[186:189], v[16:19]
	v_mfma_f32_16x16x32_bf16 v[8:11], v[210:213], v[186:189], v[8:11]
	v_mfma_f32_16x16x32_bf16 v[4:7], v[202:205], v[194:197], v[4:7]
	v_mfma_f32_16x16x32_bf16 v[0:3], v[210:213], v[194:197], v[0:3]
	v_mfma_f32_16x16x32_bf16 v[48:51], v[206:209], v[174:177], v[48:51]
	ds_read_b128 v[170:173], v151 offset:32768
	v_mfma_f32_16x16x32_bf16 v[40:43], v[214:217], v[174:177], v[40:43]
	v_mfma_f32_16x16x32_bf16 v[32:35], v[206:209], v[182:185], v[32:35]
	ds_read_b128 v[178:181], v151 offset:34816
	v_mfma_f32_16x16x32_bf16 v[24:27], v[214:217], v[182:185], v[24:27]
	v_mfma_f32_16x16x32_bf16 v[16:19], v[206:209], v[190:193], v[16:19]
	ds_read_b128 v[186:189], v151 offset:36864
	v_mfma_f32_16x16x32_bf16 v[8:11], v[214:217], v[190:193], v[8:11]
	v_mfma_f32_16x16x32_bf16 v[4:7], v[206:209], v[198:201], v[4:7]
	ds_read_b128 v[194:197], v151 offset:38912
	v_mfma_f32_16x16x32_bf16 v[0:3], v[214:217], v[198:201], v[0:3]
	s_barrier
	s_setprio 0
	s_add_i32 s82, 0, 0x18000
	v_add_u32_e32 v153, s82, v148
	s_add_u32 s48, s48, 0x100000
	s_addc_u32 s49, s49, 0
	s_mov_b32 m0, s59
	s_nop 0
	global_load_lds_dwordx4 v134, s[48:49]
	s_mov_b32 m0, s60
	s_nop 0
	global_load_lds_dwordx4 v138, s[48:49]
	ds_read_b128 v[174:177], v151 offset:33792
	ds_read_b128 v[182:185], v151 offset:35840
	ds_read_b128 v[190:193], v151 offset:37888
	ds_read_b128 v[198:201], v151 offset:39936
	s_waitcnt lgkmcnt(8)
	s_waitcnt lgkmcnt(0)
	s_setprio 1
	v_add_u32_e32 v153, 0x1c000, v148
	s_barrier
	v_mfma_f32_16x16x32_bf16 v[124:127], v[154:157], v[170:173], v[124:127]
	v_mfma_f32_16x16x32_bf16 v[120:123], v[162:165], v[170:173], v[120:123]
	v_mfma_f32_16x16x32_bf16 v[116:119], v[154:157], v[178:181], v[116:119]
	v_mfma_f32_16x16x32_bf16 v[108:111], v[162:165], v[178:181], v[108:111]
	v_mfma_f32_16x16x32_bf16 v[100:103], v[154:157], v[186:189], v[100:103]
	v_mfma_f32_16x16x32_bf16 v[92:95], v[162:165], v[186:189], v[92:95]
	v_mfma_f32_16x16x32_bf16 v[84:87], v[154:157], v[194:197], v[84:87]
	v_mfma_f32_16x16x32_bf16 v[76:79], v[162:165], v[194:197], v[76:79]
	v_mfma_f32_16x16x32_bf16 v[124:127], v[158:161], v[174:177], v[124:127]
	v_mfma_f32_16x16x32_bf16 v[120:123], v[166:169], v[174:177], v[120:123]
	v_mfma_f32_16x16x32_bf16 v[116:119], v[158:161], v[182:185], v[116:119]
	v_mfma_f32_16x16x32_bf16 v[108:111], v[166:169], v[182:185], v[108:111]
	v_mfma_f32_16x16x32_bf16 v[100:103], v[158:161], v[190:193], v[100:103]
	v_mfma_f32_16x16x32_bf16 v[92:95], v[166:169], v[190:193], v[92:95]
	v_mfma_f32_16x16x32_bf16 v[84:87], v[158:161], v[198:201], v[84:87]
	v_mfma_f32_16x16x32_bf16 v[76:79], v[166:169], v[198:201], v[76:79]
	s_barrier
	s_setprio 0
	ds_read_b128 v[202:205], v153
	ds_read_b128 v[206:209], v153 offset:1024
	ds_read_b128 v[210:213], v153 offset:2048
	ds_read_b128 v[214:217], v153 offset:3072
	s_add_i32 s48, 0, 0x1c000
	s_add_i32 s49, s82, s56
	v_add_u32_e32 v153, s48, v148
	s_add_u32 s98, s46, s8
	s_addc_u32 s99, s47, s9
	s_mov_b32 m0, s49
	s_nop 0
	global_load_lds_dwordx4 v136, s[98:99]
	s_add_i32 m0, s49, 0x2000
	s_nop 0
	global_load_lds_dwordx4 v140, s[98:99]
	s_waitcnt lgkmcnt(0)
	s_setprio 1
	s_barrier
	v_mfma_f32_16x16x32_bf16 v[112:115], v[202:205], v[170:173], v[112:115]
	v_mfma_f32_16x16x32_bf16 v[104:107], v[210:213], v[170:173], v[104:107]
	v_mfma_f32_16x16x32_bf16 v[96:99], v[202:205], v[178:181], v[96:99]
	v_mfma_f32_16x16x32_bf16 v[88:91], v[210:213], v[178:181], v[88:91]
	v_mfma_f32_16x16x32_bf16 v[80:83], v[202:205], v[186:189], v[80:83]
	v_mfma_f32_16x16x32_bf16 v[72:75], v[210:213], v[186:189], v[72:75]
	v_mfma_f32_16x16x32_bf16 v[68:71], v[202:205], v[194:197], v[68:71]
	v_mfma_f32_16x16x32_bf16 v[64:67], v[210:213], v[194:197], v[64:67]
	v_mfma_f32_16x16x32_bf16 v[112:115], v[206:209], v[174:177], v[112:115]
	ds_read_b128 v[170:173], v151 offset:49152
	v_mfma_f32_16x16x32_bf16 v[104:107], v[214:217], v[174:177], v[104:107]
	v_mfma_f32_16x16x32_bf16 v[96:99], v[206:209], v[182:185], v[96:99]
	ds_read_b128 v[178:181], v151 offset:51200
	v_mfma_f32_16x16x32_bf16 v[88:91], v[214:217], v[182:185], v[88:91]
	v_mfma_f32_16x16x32_bf16 v[80:83], v[206:209], v[190:193], v[80:83]
	ds_read_b128 v[186:189], v151 offset:53248
	v_mfma_f32_16x16x32_bf16 v[72:75], v[214:217], v[190:193], v[72:75]
	v_mfma_f32_16x16x32_bf16 v[68:71], v[206:209], v[198:201], v[68:71]
	ds_read_b128 v[194:197], v151 offset:55296
	v_mfma_f32_16x16x32_bf16 v[64:67], v[214:217], v[198:201], v[64:67]
	s_barrier
	s_setprio 0
	s_mov_b32 m0, s62
	s_add_u32 s100, s100, s8
	s_addc_u32 s101, s101, s9
	global_load_lds_dwordx4 v134, s[100:101]
	s_mov_b32 m0, s63
	s_nop 0
	global_load_lds_dwordx4 v138, s[100:101]
	ds_read_b128 v[174:177], v151 offset:50176
	ds_read_b128 v[182:185], v151 offset:52224
	ds_read_b128 v[190:193], v151 offset:54272
	ds_read_b128 v[198:201], v151 offset:56320
	s_waitcnt vmcnt(8)
	s_waitcnt lgkmcnt(0)
	s_setprio 1
	s_barrier
; #define PG8_STAGE(bufoff, gbase, voff) do { _Pragma("unroll") for (int _i = 0; _i < 2; ++_i) \
;         __builtin_amdgcn_global_load_lds((const unsigned*)((const char*)(gbase) + (voff)[_i]), (LAS unsigned*)(lds + (bufoff) + ldsw + _i * 8192), 16, 0, 0); } while (0)
; #define PG8_LDA(dst, b, h) do { _Pragma("unroll") for (int m = 0; m < 4; ++m) _Pragma("unroll") for (int k = 0; k < 2; ++k) dst[m][k] = *(const LAS bf16x8*)(lds + PG8_SA(b, h) + aoff + m * 2048 + k * 1024); } while (0)
; #define PG8_LDB(dst, b, h) do { _Pragma("unroll") for (int n = 0; n < 2; ++n) _Pragma("unroll") for (int k = 0; k < 2; ++k) dst[n][k] = *(const LAS bf16x8*)(lds + PG8_SB(b, h) + boff + n * 2048 + k * 1024); } while (0)
; #define PG8_MMA(ai, bj, At, Bt) do { __builtin_amdgcn_s_setprio(1); _Pragma("unroll") for (int m = 0; m < 4; ++m) _Pragma("unroll") for (int n = 0; n < 2; ++n) _Pragma("unroll") for (int k = 0; k < 2; ++k) \
;         acc[ai][bj][m][n] = __builtin_amdgcn_mfma_f32_16x16x32_bf16(Bt[n][k], At[m][k], acc[ai][bj][m][n], 0, 0, 0); __builtin_amdgcn_s_setprio(0); } while (0)
; #define PG8_WAIT_V(n) asm volatile("s_waitcnt vmcnt(" #n ")" ::: "memory")
; #define PG8_WAIT_L(n) asm volatile("s_waitcnt lgkmcnt(" #n ")" ::: "memory")
; #define PG8_BAR __builtin_amdgcn_s_barrier()
; #define PG8_SCHED __builtin_amdgcn_sched_barrier(0)
; template <class Epi, class Job>
; __device__ __forceinline__ void gemm_phase(LAS unsigned char* lds, const Job& S, const Epi& E) {
;     ...
;             PG8_LDB(B0, 1, 0); PG8_SCHED; PG8_LDA(At, 1, 0); PG8_STAGE(PG8_SA(0, 1), a2 + hstepA, voffA);
;             PG8_WAIT_L(8); PG8_BAR; PG8_WAIT_L(0); PG8_MMA(0, 0, At, B0); PG8_BAR; PG8_SCHED;
;             PG8_LDB(B1, 1, 1); PG8_STAGE(PG8_SB(1, 0), b3, voffB);
;             PG8_BAR; PG8_WAIT_L(0); PG8_MMA(0, 1, At, B1); PG8_BAR;
;             PG8_LDA(At, 1, 1); PG8_STAGE(PG8_SA(1, 0), a3, voffA);
;             PG8_BAR; PG8_WAIT_L(0); PG8_MMA(1, 0, At, B0); PG8_BAR; PG8_SCHED;
;             PG8_STAGE(PG8_SB(1, 1), b3 + hstepB, voffB);
;             PG8_WAIT_V(6); PG8_BAR; PG8_MMA(1, 1, At, B1); PG8_BAR;
;         }
	v_mfma_f32_16x16x32_bf16 v[60:63], v[154:157], v[170:173], v[60:63]
	v_mfma_f32_16x16x32_bf16 v[56:59], v[162:165], v[170:173], v[56:59]
	v_mfma_f32_16x16x32_bf16 v[52:55], v[154:157], v[178:181], v[52:55]
	v_mfma_f32_16x16x32_bf16 v[44:47], v[162:165], v[178:181], v[44:47]
	v_mfma_f32_16x16x32_bf16 v[36:39], v[154:157], v[186:189], v[36:39]
	v_mfma_f32_16x16x32_bf16 v[28:31], v[162:165], v[186:189], v[28:31]
	v_mfma_f32_16x16x32_bf16 v[20:23], v[154:157], v[194:197], v[20:23]
	v_mfma_f32_16x16x32_bf16 v[12:15], v[162:165], v[194:197], v[12:15]
	v_mfma_f32_16x16x32_bf16 v[60:63], v[158:161], v[174:177], v[60:63]
	v_mfma_f32_16x16x32_bf16 v[56:59], v[166:169], v[174:177], v[56:59]
	v_mfma_f32_16x16x32_bf16 v[52:55], v[158:161], v[182:185], v[52:55]
	v_mfma_f32_16x16x32_bf16 v[44:47], v[166:169], v[182:185], v[44:47]
	v_mfma_f32_16x16x32_bf16 v[36:39], v[158:161], v[190:193], v[36:39]
	v_mfma_f32_16x16x32_bf16 v[28:31], v[166:169], v[190:193], v[28:31]
	v_mfma_f32_16x16x32_bf16 v[20:23], v[158:161], v[198:201], v[20:23]
	v_mfma_f32_16x16x32_bf16 v[12:15], v[166:169], v[198:201], v[12:15]
	s_barrier
	s_setprio 0
	s_add_u32 s46, s46, 0x100080
	s_addc_u32 s47, s47, 0
	s_add_i32 s48, s48, s56
	s_mov_b32 m0, s48
	s_nop 0
	global_load_lds_dwordx4 v136, s[46:47]
	s_add_i32 m0, s48, 0x2000
	s_nop 0
	global_load_lds_dwordx4 v140, s[46:47]
	ds_read_b128 v[154:157], v150
	ds_read_b128 v[158:161], v150 offset:1024
	ds_read_b128 v[162:165], v150 offset:2048
	ds_read_b128 v[166:169], v150 offset:3072
	s_waitcnt vmcnt(6)
	s_setprio 1
	s_barrier
	v_mfma_f32_16x16x32_bf16 v[48:51], v[202:205], v[170:173], v[48:51]
	v_mfma_f32_16x16x32_bf16 v[40:43], v[210:213], v[170:173], v[40:43]
	v_mfma_f32_16x16x32_bf16 v[32:35], v[202:205], v[178:181], v[32:35]
	v_mfma_f32_16x16x32_bf16 v[24:27], v[210:213], v[178:181], v[24:27]
	v_mfma_f32_16x16x32_bf16 v[16:19], v[202:205], v[186:189], v[16:19]
	v_mfma_f32_16x16x32_bf16 v[8:11], v[210:213], v[186:189], v[8:11]
	v_mfma_f32_16x16x32_bf16 v[4:7], v[202:205], v[194:197], v[4:7]
	v_mfma_f32_16x16x32_bf16 v[0:3], v[210:213], v[194:197], v[0:3]
	v_mfma_f32_16x16x32_bf16 v[48:51], v[206:209], v[174:177], v[48:51]
	ds_read_b128 v[170:173], v151
	v_mfma_f32_16x16x32_bf16 v[40:43], v[214:217], v[174:177], v[40:43]
	v_mfma_f32_16x16x32_bf16 v[32:35], v[206:209], v[182:185], v[32:35]
	ds_read_b128 v[178:181], v151 offset:2048
	v_mfma_f32_16x16x32_bf16 v[24:27], v[214:217], v[182:185], v[24:27]
	v_mfma_f32_16x16x32_bf16 v[16:19], v[206:209], v[190:193], v[16:19]
	ds_read_b128 v[186:189], v151 offset:4096
	v_mfma_f32_16x16x32_bf16 v[8:11], v[214:217], v[190:193], v[8:11]
	v_mfma_f32_16x16x32_bf16 v[4:7], v[206:209], v[198:201], v[4:7]
	ds_read_b128 v[194:197], v151 offset:6144
	v_mfma_f32_16x16x32_bf16 v[0:3], v[214:217], v[198:201], v[0:3]
	s_barrier
	s_setprio 0
	s_add_i32 s81, s81, 2
	s_add_u32 s36, s36, 0x100
	s_addc_u32 s37, s37, 0
	s_add_u32 s79, s79, 0x100
	s_addc_u32 s80, s80, 0
	s_cmp_gt_u32 s81, 61
	s_cbranch_scc0 .LBB0_457
; __device__ __forceinline__ unsigned cvt_pk_bf16(float lo, float hi) { unsigned r; asm volatile("v_cvt_pk_bf16_f32 %0, %1, %2" : "=v"(r) : "v"(lo), "v"(hi)); return r; }
; #define PG8_WAIT_V(n) asm volatile("s_waitcnt vmcnt(" #n ")" ::: "memory")
; #define PG8_BAR __builtin_amdgcn_s_barrier()
;     __device__ __forceinline__ void operator()(const f32x4 (&acc)[2][2][4][2], const Unit& u, int wr, int wc, int fr, int fq) const {
;     ...
;             for (int m = 0; m < 4; ++m) { bf16_t* rowp = O + (size_t)(row0 + ai * HALF + m * 16) * ldc + col0;
; #pragma unroll
;                 for (int bj = 0; bj < 2; ++bj) { const f32x4 v0 = acc[ai][bj][m][0], v1 = acc[ai][bj][m][1];
;                     u32x4 w; w.x = cvt_pk_bf16(v0[0], v0[1]); w.y = cvt_pk_bf16(v0[2], v0[3]); w.z = cvt_pk_bf16(v1[0], v1[1]); w.w = cvt_pk_bf16(v1[2], v1[3]);
;                     if (nt) __builtin_nontemporal_store(w, (u32x4*)(rowp + bj * HALF)); else *(u32x4*)(rowp + bj * HALF) = w; } }
; template <class Epi, class Job>
; __device__ __forceinline__ void gemm_phase(LAS unsigned char* lds, const Job& S, const Epi& E) {
;     ...
;         E(acc, cur, wr, wc, fr, fq);
;         if (!has_next) break;
; #pragma unroll
;         for (int a = 0; a < 2; ++a)
; #pragma unroll
;             for (int b = 0; b < 2; ++b)
; #pragma unroll
;                 for (int m = 0; m < 4; ++m)
; #pragma unroll
;                     for (int n = 0; n < 2; ++n) acc[a][b][m][n] = (f32x4){0.f, 0.f, 0.f, 0.f};
;         cur = nxt; cA = nA; cB = nB; ++ui;
;     }
;     PG8_WAIT_V(0);
;     if (wr == 0) PG8_BAR;
;     PG8_BAR;
	s_waitcnt lgkmcnt(0)
	v_add_u32_e32 v146, s78, v131
	v_ashrrev_i32_e32 v147, 31, v146
	v_add_u32_e32 v154, s77, v149
	v_lshlrev_b64 v[146:147], 13, v[146:147]
	v_ashrrev_i32_e32 v155, 31, v154
	v_lshl_add_u64 v[146:147], s[18:19], 0, v[146:147]
	v_lshl_add_u64 v[146:147], v[154:155], 1, v[146:147]
	v_cvt_pk_bf16_f32 v124, v124, v125
	v_cvt_pk_bf16_f32 v125, v126, v127
	v_cvt_pk_bf16_f32 v126, v120, v121
	v_cvt_pk_bf16_f32 v127, v122, v123
	global_store_dwordx4 v[146:147], v[124:127], off
	v_cvt_pk_bf16_f32 v112, v112, v113
	v_cvt_pk_bf16_f32 v113, v114, v115
	v_cvt_pk_bf16_f32 v114, v104, v105
	v_cvt_pk_bf16_f32 v115, v106, v107
	global_store_dwordx4 v[146:147], v[112:115], off offset:256
	v_cvt_pk_bf16_f32 v104, v116, v117
	v_cvt_pk_bf16_f32 v105, v118, v119
	v_cvt_pk_bf16_f32 v106, v108, v109
	v_add_co_u32_e32 v108, vcc, s68, v146
	s_nop 0
	v_lshl_add_u64 v[112:113], v[146:147], 0, s[10:11]
	v_addc_co_u32_e32 v109, vcc, 0, v147, vcc
	v_cvt_pk_bf16_f32 v107, v110, v111
	global_store_dwordx4 v[108:109], v[104:107], off
	v_cvt_pk_bf16_f32 v96, v96, v97
	v_cvt_pk_bf16_f32 v97, v98, v99
	v_cvt_pk_bf16_f32 v98, v88, v89
	v_cvt_pk_bf16_f32 v99, v90, v91
	global_store_dwordx4 v[112:113], v[96:99], off offset:256
	v_cvt_pk_bf16_f32 v88, v100, v101
	v_cvt_pk_bf16_f32 v89, v102, v103
	v_cvt_pk_bf16_f32 v90, v92, v93
	v_add_co_u32_e32 v92, vcc, s69, v146
	s_nop 0
	v_lshl_add_u64 v[96:97], v[146:147], 0, s[12:13]
	v_addc_co_u32_e32 v93, vcc, 0, v147, vcc
	v_cvt_pk_bf16_f32 v91, v94, v95
	global_store_dwordx4 v[92:93], v[88:91], off
	v_cvt_pk_bf16_f32 v80, v80, v81
	v_cvt_pk_bf16_f32 v81, v82, v83
	v_cvt_pk_bf16_f32 v82, v72, v73
	v_cvt_pk_bf16_f32 v83, v74, v75
	global_store_dwordx4 v[96:97], v[80:83], off offset:256
	v_cvt_pk_bf16_f32 v72, v84, v85
	v_cvt_pk_bf16_f32 v73, v86, v87
	v_cvt_pk_bf16_f32 v74, v76, v77
	v_add_co_u32_e32 v76, vcc, s70, v146
	s_nop 0
	v_lshl_add_u64 v[80:81], v[146:147], 0, s[20:21]
	v_addc_co_u32_e32 v77, vcc, 0, v147, vcc
	v_cvt_pk_bf16_f32 v75, v78, v79
	global_store_dwordx4 v[76:77], v[72:75], off
	v_cvt_pk_bf16_f32 v68, v68, v69
	v_cvt_pk_bf16_f32 v69, v70, v71
	v_cvt_pk_bf16_f32 v70, v64, v65
	v_cvt_pk_bf16_f32 v71, v66, v67
	global_store_dwordx4 v[80:81], v[68:71], off offset:256
	v_cvt_pk_bf16_f32 v60, v60, v61
	v_cvt_pk_bf16_f32 v61, v62, v63
	v_cvt_pk_bf16_f32 v62, v56, v57
	v_add_co_u32_e32 v56, vcc, s71, v146
	v_lshl_add_u64 v[64:65], v[146:147], 0, s[6:7]
	s_nop 0
	v_addc_co_u32_e32 v57, vcc, 0, v147, vcc
	v_cvt_pk_bf16_f32 v63, v58, v59
	global_store_dwordx4 v[56:57], v[60:63], off
	v_cvt_pk_bf16_f32 v48, v48, v49
	v_cvt_pk_bf16_f32 v49, v50, v51
	v_cvt_pk_bf16_f32 v50, v40, v41
	v_cvt_pk_bf16_f32 v51, v42, v43
	global_store_dwordx4 v[64:65], v[48:51], off offset:256
	v_cvt_pk_bf16_f32 v40, v52, v53
	v_cvt_pk_bf16_f32 v41, v54, v55
	v_cvt_pk_bf16_f32 v42, v44, v45
	v_add_co_u32_e32 v44, vcc, s72, v146
	s_nop 0
	v_lshl_add_u64 v[48:49], v[146:147], 0, s[22:23]
	v_addc_co_u32_e32 v45, vcc, 0, v147, vcc
	v_cvt_pk_bf16_f32 v43, v46, v47
	global_store_dwordx4 v[44:45], v[40:43], off
	v_cvt_pk_bf16_f32 v32, v32, v33
	v_cvt_pk_bf16_f32 v33, v34, v35
	v_cvt_pk_bf16_f32 v34, v24, v25
	v_cvt_pk_bf16_f32 v35, v26, v27
	global_store_dwordx4 v[48:49], v[32:35], off offset:256
	v_cvt_pk_bf16_f32 v24, v36, v37
	v_cvt_pk_bf16_f32 v25, v38, v39
	v_cvt_pk_bf16_f32 v26, v28, v29
	v_add_co_u32_e32 v28, vcc, s73, v146
	s_nop 0
	v_lshl_add_u64 v[32:33], v[146:147], 0, s[24:25]
	v_addc_co_u32_e32 v29, vcc, 0, v147, vcc
	v_cvt_pk_bf16_f32 v27, v30, v31
	global_store_dwordx4 v[28:29], v[24:27], off
	v_cvt_pk_bf16_f32 v16, v16, v17
	v_cvt_pk_bf16_f32 v17, v18, v19
	v_cvt_pk_bf16_f32 v18, v8, v9
	v_cvt_pk_bf16_f32 v19, v10, v11
	global_store_dwordx4 v[32:33], v[16:19], off offset:256
	v_cvt_pk_bf16_f32 v8, v20, v21
	v_cvt_pk_bf16_f32 v9, v22, v23
	v_cvt_pk_bf16_f32 v10, v12, v13
	v_add_co_u32_e32 v12, vcc, s74, v146
	s_nop 0
	v_lshl_add_u64 v[16:17], v[146:147], 0, s[26:27]
	v_addc_co_u32_e32 v13, vcc, 0, v147, vcc
	s_and_b64 vcc, exec, s[4:5]
	s_mov_b32 s77, s76
	s_mov_b32 s78, s75
	s_mov_b64 s[46:47], s[30:31]
	s_mov_b64 s[36:37], s[28:29]
	v_cvt_pk_bf16_f32 v11, v14, v15
	global_store_dwordx4 v[12:13], v[8:11], off
	v_cvt_pk_bf16_f32 v4, v4, v5
	v_cvt_pk_bf16_f32 v5, v6, v7
	v_cvt_pk_bf16_f32 v6, v0, v1
	v_cvt_pk_bf16_f32 v7, v2, v3
	global_store_dwordx4 v[16:17], v[4:7], off offset:256
	s_cbranch_vccz .LBB0_450
	s_waitcnt vmcnt(0)
	s_cmpk_gt_u32 s50, 0xff
	s_cbranch_scc1 .LBB0_461
	s_barrier
